# second-half fragment-read lookahead in gres1/gres2/kvq added to the gemm1 k-step rewrite
# speedup vs baseline: 1.0120x; 1.0073x over previous
.LBB0_888:
	s_waitcnt vmcnt(8)
	ds_read_b128 v[134:137], v151 offset:32768
	ds_write_b128 v141, v[64:67]
	ds_write_b128 v141, v[72:75] offset:16384
	s_andn2_b64 vcc, exec, s[8:9]
	s_waitcnt lgkmcnt(2)
	v_mfma_f32_32x32x16_bf16 v[48:63], v[134:137], v[160:163], v[48:63]
	v_mfma_f32_32x32x16_bf16 v[32:47], v[134:137], v[168:171], v[32:47]
	ds_read_b128 v[134:137], v153 offset:32768
	v_mfma_f32_32x32x16_bf16 v[16:31], v[164:167], v[160:163], v[16:31]
	ds_read_b128 v[160:163], v154 offset:49152
	v_mfma_f32_32x32x16_bf16 v[0:15], v[164:167], v[168:171], v[0:15]
	ds_read_b128 v[164:167], v153 offset:36864
	ds_read_b128 v[168:171], v154 offset:53248
	ds_write_b128 v141, v[80:83] offset:4096
	ds_write_b128 v141, v[88:91] offset:20480
	s_waitcnt lgkmcnt(2)
	v_mfma_f32_32x32x16_bf16 v[48:63], v[134:137], v[160:163], v[48:63]
	v_mfma_f32_32x32x16_bf16 v[32:47], v[134:137], v[168:171], v[32:47]
	ds_read_b128 v[134:137], v155 offset:32768
	v_mfma_f32_32x32x16_bf16 v[16:31], v[164:167], v[160:163], v[16:31]
	ds_read_b128 v[160:163], v156 offset:49152
	ds_read_b128 v[152:155], v155 offset:36864
	v_mfma_f32_32x32x16_bf16 v[0:15], v[164:167], v[168:171], v[0:15]
	ds_read_b128 v[164:167], v156 offset:53248
	ds_write_b128 v141, v[96:99] offset:8192
	ds_write_b128 v141, v[104:107] offset:24576
	s_waitcnt lgkmcnt(2)
	v_mfma_f32_32x32x16_bf16 v[48:63], v[134:137], v[160:163], v[48:63]
	v_mfma_f32_32x32x16_bf16 v[32:47], v[134:137], v[164:167], v[32:47]
	ds_read_b128 v[134:137], v157 offset:32768
	v_mfma_f32_32x32x16_bf16 v[16:31], v[152:155], v[160:163], v[16:31]
	v_mfma_f32_32x32x16_bf16 v[0:15], v[152:155], v[164:167], v[0:15]
	ds_read_b128 v[152:155], v158 offset:49152
	ds_read_b128 v[160:163], v157 offset:36864
	ds_read_b128 v[156:159], v158 offset:53248
	ds_write_b128 v141, v[112:115] offset:12288
	ds_write_b128 v141, v[120:123] offset:28672
	s_waitcnt lgkmcnt(2)
	v_mfma_f32_32x32x16_bf16 v[48:63], v[134:137], v[152:155], v[48:63]
	v_mfma_f32_32x32x16_bf16 v[32:47], v[134:137], v[156:159], v[32:47]
	v_mfma_f32_32x32x16_bf16 v[16:31], v[160:163], v[152:155], v[16:31]
	v_mfma_f32_32x32x16_bf16 v[0:15], v[160:163], v[156:159], v[0:15]
	s_branch .LBB0_883

.LBB0_1012:
	s_waitcnt vmcnt(8)
	ds_read_b128 v[192:195], v153 offset:32768
	ds_write_b128 v135, v[64:67]
	ds_write_b128 v135, v[72:75] offset:16384
	s_andn2_b64 vcc, exec, s[8:9]
	s_waitcnt lgkmcnt(2)
	v_mfma_f32_32x32x16_bf16 v[32:47], v[192:195], v[218:221], v[32:47]
	v_mfma_f32_32x32x16_bf16 v[48:63], v[192:195], v[226:229], v[48:63]
	ds_read_b128 v[192:195], v157 offset:32768
	v_mfma_f32_32x32x16_bf16 v[0:15], v[222:225], v[218:221], v[0:15]
	ds_read_b128 v[218:221], v159 offset:49152
	v_mfma_f32_32x32x16_bf16 v[16:31], v[222:225], v[226:229], v[16:31]
	ds_read_b128 v[222:225], v157 offset:36864
	ds_read_b128 v[226:229], v159 offset:53248
	ds_write_b128 v135, v[80:83] offset:4096
	ds_write_b128 v135, v[88:91] offset:20480
	s_waitcnt lgkmcnt(2)
	v_mfma_f32_32x32x16_bf16 v[32:47], v[192:195], v[218:221], v[32:47]
	v_mfma_f32_32x32x16_bf16 v[48:63], v[192:195], v[226:229], v[48:63]
	ds_read_b128 v[192:195], v161 offset:32768
	v_mfma_f32_32x32x16_bf16 v[0:15], v[222:225], v[218:221], v[0:15]
	ds_read_b128 v[218:221], v163 offset:49152
	v_mfma_f32_32x32x16_bf16 v[16:31], v[222:225], v[226:229], v[16:31]
	ds_read_b128 v[222:225], v161 offset:36864
	ds_read_b128 v[226:229], v163 offset:53248
	ds_write_b128 v135, v[96:99] offset:8192
	ds_write_b128 v135, v[104:107] offset:24576
	s_waitcnt lgkmcnt(2)
	v_mfma_f32_32x32x16_bf16 v[32:47], v[192:195], v[218:221], v[32:47]
	v_mfma_f32_32x32x16_bf16 v[48:63], v[192:195], v[226:229], v[48:63]
	ds_read_b128 v[192:195], v165 offset:32768
	v_mfma_f32_32x32x16_bf16 v[0:15], v[222:225], v[218:221], v[0:15]
	ds_read_b128 v[218:221], v167 offset:49152
	v_mfma_f32_32x32x16_bf16 v[16:31], v[222:225], v[226:229], v[16:31]
	ds_read_b128 v[222:225], v165 offset:36864
	ds_read_b128 v[226:229], v167 offset:53248
	ds_write_b128 v135, v[112:115] offset:12288
	ds_write_b128 v135, v[120:123] offset:28672
	s_waitcnt lgkmcnt(2)
	v_mfma_f32_32x32x16_bf16 v[32:47], v[192:195], v[218:221], v[32:47]
	v_mfma_f32_32x32x16_bf16 v[48:63], v[192:195], v[226:229], v[48:63]
	v_mfma_f32_32x32x16_bf16 v[0:15], v[222:225], v[218:221], v[0:15]
	v_mfma_f32_32x32x16_bf16 v[16:31], v[222:225], v[226:229], v[16:31]
	s_branch .LBB0_1007

.LBB0_1510:
	s_waitcnt vmcnt(8)
	ds_read_b128 v[134:137], v145 offset:32768
	ds_write_b128 v138, v[64:67]
	ds_write_b128 v138, v[72:75] offset:16384
	s_andn2_b64 vcc, exec, s[6:7]
	s_waitcnt lgkmcnt(2)
	v_mfma_f32_32x32x16_bf16 v[48:63], v[134:137], v[154:157], v[48:63]
	v_mfma_f32_32x32x16_bf16 v[32:47], v[134:137], v[162:165], v[32:47]
	ds_read_b128 v[134:137], v147 offset:32768
	v_mfma_f32_32x32x16_bf16 v[16:31], v[158:161], v[154:157], v[16:31]
	ds_read_b128 v[154:157], v148 offset:49152
	v_mfma_f32_32x32x16_bf16 v[0:15], v[158:161], v[162:165], v[0:15]
	ds_read_b128 v[158:161], v147 offset:36864
	ds_read_b128 v[162:165], v148 offset:53248
	ds_write_b128 v138, v[80:83] offset:4096
	ds_write_b128 v138, v[88:91] offset:20480
	s_waitcnt lgkmcnt(2)
	v_mfma_f32_32x32x16_bf16 v[48:63], v[134:137], v[154:157], v[48:63]
	v_mfma_f32_32x32x16_bf16 v[32:47], v[134:137], v[162:165], v[32:47]
	ds_read_b128 v[134:137], v149 offset:32768
	v_mfma_f32_32x32x16_bf16 v[16:31], v[158:161], v[154:157], v[16:31]
	ds_read_b128 v[154:157], v150 offset:49152
	ds_read_b128 v[146:149], v149 offset:36864
	v_mfma_f32_32x32x16_bf16 v[0:15], v[158:161], v[162:165], v[0:15]
	ds_read_b128 v[158:161], v150 offset:53248
	ds_write_b128 v138, v[96:99] offset:8192
	ds_write_b128 v138, v[104:107] offset:24576
	s_waitcnt lgkmcnt(2)
	v_mfma_f32_32x32x16_bf16 v[48:63], v[134:137], v[154:157], v[48:63]
	v_mfma_f32_32x32x16_bf16 v[32:47], v[134:137], v[158:161], v[32:47]
	ds_read_b128 v[134:137], v151 offset:32768
	v_mfma_f32_32x32x16_bf16 v[16:31], v[146:149], v[154:157], v[16:31]
	v_mfma_f32_32x32x16_bf16 v[0:15], v[146:149], v[158:161], v[0:15]
	ds_read_b128 v[146:149], v152 offset:49152
	ds_read_b128 v[154:157], v151 offset:36864
	ds_read_b128 v[150:153], v152 offset:53248
	ds_write_b128 v138, v[112:115] offset:12288
	ds_write_b128 v138, v[120:123] offset:28672
	s_waitcnt lgkmcnt(2)
	v_mfma_f32_32x32x16_bf16 v[48:63], v[134:137], v[146:149], v[48:63]
	v_mfma_f32_32x32x16_bf16 v[32:47], v[134:137], v[150:153], v[32:47]
	v_mfma_f32_32x32x16_bf16 v[16:31], v[154:157], v[146:149], v[16:31]
	v_mfma_f32_32x32x16_bf16 v[0:15], v[154:157], v[150:153], v[0:15]
	s_branch .LBB0_1505
